# v15 + grid barrier: leader no longer increments the unused per-XCD generation word
# speedup vs baseline: 1.0193x; 1.0002x over previous
; DI unsigned xb_ld(unsigned* p) { return __hip_atomic_load(p, __ATOMIC_RELAXED, __HIP_MEMORY_SCOPE_AGENT); }
; DI unsigned xb_add(unsigned* p, unsigned v) { return __hip_atomic_fetch_add(p, v, __ATOMIC_RELAXED, __HIP_MEMORY_SCOPE_AGENT); }
; #define XB_SPIN(cond, bar) do { unsigned _sp = 0; while (cond) { __builtin_amdgcn_s_sleep(1); \
;     if ((++_sp & 255u) == 0u) { if (xb_ld(&(bar)[XB_TMO])) break; if (_sp > XB_SPIN_CAP) { atomicAdd(&(bar)[XB_TMO], 1u); break; } } } } while (0)
; DI void xcd_barrier(int wv, unsigned* bar0, volatile LAS unsigned* st) {
;     ...
;         if (old + 1u == (gen + 1u) * nloc) {
;             __builtin_amdgcn_fence(__ATOMIC_RELEASE, "agent");
;             asm volatile("s_waitcnt vmcnt(0)" ::: "memory");
;             const unsigned og = xb_add(&bar[XB_TOP], 1u);
;             const unsigned tg = og / nx;
;             if (og + 1u == (tg + 1u) * nx) xb_add(&bar[XB_TOPGEN], 1u);
;             else XB_SPIN(xb_ld(&bar[XB_TOPGEN]) == tg, bar);
;             __builtin_amdgcn_fence(__ATOMIC_ACQUIRE, "agent");
;             xb_add(&bar[XB_XGEN(x)], 1u);
;             asm volatile("s_waitcnt vmcnt(0)" ::: "memory");
.LBB0_601:
	s_or_b64 exec, exec, s[0:1]
	v_mov_b32_e32 v0, s23
	v_add_co_u32_e32 v0, vcc, 0x2000, v0
	v_mov_b32_e32 v1, s22
	s_nop 0
	v_addc_co_u32_e32 v1, vcc, 0, v1, vcc
	v_mov_b32_e32 v2, 1
	s_waitcnt vmcnt(0) lgkmcnt(0)
	buffer_inv sc1
	s_waitcnt vmcnt(0)
